# GLA step top: counted vmcnt(2) so the previous step's two output stores are not waited for
# speedup vs baseline: 1.0025x; 1.0025x over previous
; #define LAS __attribute__((address_space(3)))
; __device__ __forceinline__ void gla_unit(LAS char* lds0, int b, int h, int dvh, bf16_t* Z, bf16_t* OT, const float* afw, const float* afb, const float* abw, const float* abb, bool dry) {
;     ...
;     for (int s = 0; s < 36; ++s) {
;         const int c = GLA_CHUNK(s);
;         const size_t rbase = (size_t)b * TOK + 64 * c;
;         const int other_step = dir ? c : (c < 4 ? 3 - c : 39 - c);
;         const bool second = s > other_step;
;         *(LAS u32x4*)(lds + G_Q + lr * GP + lc * 16) = pq0; *(LAS u32x4*)(lds + G_Q + (lr + 32) * GP + lc * 16) = pq1;
;         *(LAS u32x4*)(lds + G_K + lr * GP + lc * 16) = pk0; *(LAS u32x4*)(lds + G_K + (lr + 32) * GP + lc * 16) = pk1;
;         *(LAS u32x4*)(lds + G_V + lr * GP + lc * 16) = pv0; *(LAS u32x4*)(lds + G_V + (lr + 32) * GP + lc * 16) = pv1;
;         *(LAS u32x2*)(lds + G_A16 + ar * 32 + ac * 8) = pa;
;         __syncthreads();
;         if (s + 1 < 36) GLA_PREFETCH(s + 1);
.LBB0_403:
	s_add_i32 s28, s76, 1
	v_add_u32_e32 v171, v115, v116
	s_cmp_eq_u32 s76, 0
	s_cbranch_scc1 .Lg7_old
	s_waitcnt vmcnt(2)
	ds_write_b64 v155, v[126:127] offset:64512
	s_branch .Lg7_join
